# OUT epilogues (even and odd layers): residual/gate loads of each 8-tile group issued up front, counted waits
# speedup vs baseline: 1.0121x; 1.0016x over previous
.LBB0_658:
	v_lshrrev_b32_e32 v36, 12, v40
	v_add_u32_e32 v36, 1, v36
	v_cndmask_b32_e64 v36, v36, 0, s[0:1]
	v_add_u32_e32 v40, s34, v36
	v_mov_b64_e32 v[36:37], s[20:21]
	v_mad_u64_u32 v[36:37], s[0:1], v40, s29, v[36:37]
	v_lshl_add_u64 v[44:45], v[36:37], 0, s[8:9]
	v_lshl_add_u64 v[46:47], v[34:35], 0, v[0:1]
	v_lshl_add_u64 v[40:41], v[44:45], 0, v[0:1]
	v_lshl_add_u64 v[38:39], v[38:39], 0, v[0:1]
	global_load_dwordx4 v[170:173], v[46:47], off
	global_load_dwordx4 v[204:207], v[40:41], off
	global_load_dwordx4 v[174:177], v[46:47], off offset:64
	global_load_dwordx4 v[216:219], v[40:41], off offset:64
	global_load_dwordx4 v[180:183], v[46:47], off offset:128
	global_load_dwordx4 v[226:229], v[40:41], off offset:128
	global_load_dwordx4 v[184:187], v[46:47], off offset:192
	global_load_dwordx4 v[230:233], v[40:41], off offset:192
	global_load_dwordx4 v[188:191], v[46:47], off offset:256
	global_load_dwordx4 v[234:237], v[40:41], off offset:256
	global_load_dwordx4 v[192:195], v[46:47], off offset:320
	global_load_dwordx4 v[238:241], v[40:41], off offset:320
	global_load_dwordx4 v[196:199], v[46:47], off offset:384
	global_load_dwordx4 v[242:245], v[40:41], off offset:384
	global_load_dwordx4 v[200:203], v[46:47], off offset:448
	global_load_dwordx4 v[246:249], v[40:41], off offset:448
	v_lshl_add_u64 v[48:49], v[44:45], 0, v[118:119]
	s_add_i32 s46, s46, s76
	s_add_i32 s35, s35, s95
	s_cmpk_gt_u32 s46, 0x5f
	s_waitcnt vmcnt(14)
	v_pk_fma_f32 v[32:33], v[32:33], v[206:207], v[172:173]
	v_pk_fma_f32 v[30:31], v[30:31], v[204:205], v[170:171]
	global_store_dwordx4 v[38:39], v[30:33], off
	s_nop 1
	s_nop 0
	v_lshl_add_u64 v[40:41], v[44:45], 0, v[122:123]
	s_waitcnt vmcnt(13)
	v_pk_fma_f32 v[28:29], v[28:29], v[218:219], v[176:177]
	v_pk_fma_f32 v[26:27], v[26:27], v[216:217], v[174:175]
	global_store_dwordx4 v[38:39], v[26:29], off offset:64
	s_nop 1
	s_nop 0
	v_lshl_add_u64 v[34:35], v[44:45], 0, v[124:125]
	s_waitcnt vmcnt(12)
	v_pk_fma_f32 v[24:25], v[24:25], v[228:229], v[182:183]
	v_pk_fma_f32 v[22:23], v[22:23], v[226:227], v[180:181]
	global_store_dwordx4 v[38:39], v[22:25], off offset:128
	s_nop 1
	s_nop 0
	v_lshl_add_u64 v[30:31], v[44:45], 0, v[114:115]
	s_waitcnt vmcnt(11)
	v_pk_fma_f32 v[20:21], v[20:21], v[232:233], v[186:187]
	v_pk_fma_f32 v[18:19], v[18:19], v[230:231], v[184:185]
	global_store_dwordx4 v[38:39], v[18:21], off offset:192
	s_nop 1
	s_nop 0
	v_lshl_add_u64 v[26:27], v[44:45], 0, v[110:111]
	s_waitcnt vmcnt(10)
	v_pk_fma_f32 v[16:17], v[16:17], v[236:237], v[190:191]
	v_pk_fma_f32 v[14:15], v[14:15], v[234:235], v[188:189]
	global_store_dwordx4 v[38:39], v[14:17], off offset:256
	s_nop 1
	s_nop 0
	v_lshl_add_u64 v[22:23], v[44:45], 0, v[106:107]
	s_waitcnt vmcnt(9)
	v_pk_fma_f32 v[12:13], v[12:13], v[240:241], v[194:195]
	v_pk_fma_f32 v[10:11], v[10:11], v[238:239], v[192:193]
	global_store_dwordx4 v[38:39], v[10:13], off offset:320
	s_nop 1
	s_nop 0
	v_lshl_add_u64 v[18:19], v[44:45], 0, v[102:103]
	s_waitcnt vmcnt(8)
	v_pk_fma_f32 v[8:9], v[8:9], v[244:245], v[198:199]
	v_pk_fma_f32 v[6:7], v[6:7], v[242:243], v[196:197]
	global_store_dwordx4 v[38:39], v[6:9], off offset:384
	s_nop 1
	s_nop 0
	s_waitcnt vmcnt(7)
	v_pk_fma_f32 v[4:5], v[4:5], v[248:249], v[202:203]
	v_pk_fma_f32 v[2:3], v[2:3], v[246:247], v[200:201]
	global_store_dwordx4 v[38:39], v[2:5], off offset:448
	s_nop 1
	s_cbranch_scc1 .LBB0_686

.LBB0_669:
	v_lshrrev_b32_e32 v0, 12, v0
	s_add_u32 s20, s90, s8
	v_add_u32_e32 v0, 1, v0
	s_addc_u32 s21, s91, s9
	v_cndmask_b32_e64 v0, v0, 0, s[0:1]
	v_lshrrev_b32_e32 v121, 2, v124
	v_add_u32_e32 v0, s34, v0
	v_mov_b64_e32 v[124:125], s[20:21]
	v_and_or_b32 v121, v121, 12, s10
	v_mad_u64_u32 v[124:125], s[0:1], v0, s29, v[124:125]
	s_mov_b64 s[8:9], 0x5700
	s_waitcnt vmcnt(9)
	v_lshl_add_u64 v[128:129], v[124:125], 0, s[8:9]
	v_lshlrev_b32_e32 v0, 2, v121
	s_waitcnt vmcnt(8)
	v_lshl_add_u64 v[130:131], v[122:123], 0, v[0:1]
	v_lshl_add_u64 v[126:127], v[128:129], 0, v[0:1]
	global_load_dwordx4 v[170:173], v[130:131], off
	global_load_dwordx4 v[204:207], v[126:127], off
	global_load_dwordx4 v[174:177], v[130:131], off offset:64
	global_load_dwordx4 v[216:219], v[126:127], off offset:64
	global_load_dwordx4 v[180:183], v[130:131], off offset:128
	global_load_dwordx4 v[226:229], v[126:127], off offset:128
	global_load_dwordx4 v[184:187], v[130:131], off offset:192
	global_load_dwordx4 v[230:233], v[126:127], off offset:192
	global_load_dwordx4 v[188:191], v[130:131], off offset:256
	global_load_dwordx4 v[234:237], v[126:127], off offset:256
	global_load_dwordx4 v[192:195], v[130:131], off offset:320
	global_load_dwordx4 v[238:241], v[126:127], off offset:320
	global_load_dwordx4 v[196:199], v[130:131], off offset:384
	global_load_dwordx4 v[242:245], v[126:127], off offset:384
	global_load_dwordx4 v[200:203], v[130:131], off offset:448
	global_load_dwordx4 v[246:249], v[126:127], off offset:448
	v_lshl_add_u64 v[126:127], v[118:119], 0, v[0:1]
	v_or_b32_e32 v118, 16, v121
	v_lshlrev_b32_e32 v118, 2, v118
	v_mov_b32_e32 v119, v1
	v_lshl_add_u64 v[132:133], v[128:129], 0, v[118:119]
	s_and_b64 vcc, exec, s[40:41]
	s_waitcnt vmcnt(14)
	v_pk_fma_f32 v[124:125], v[168:169], v[206:207], v[172:173]
	v_pk_fma_f32 v[122:123], v[166:167], v[204:205], v[170:171]
	global_store_dwordx4 v[126:127], v[122:125], off
	s_nop 1
	s_nop 0
	s_waitcnt vmcnt(13)
	v_pk_fma_f32 v[124:125], v[148:149], v[218:219], v[176:177]
	v_pk_fma_f32 v[122:123], v[146:147], v[216:217], v[174:175]
	global_store_dwordx4 v[126:127], v[122:125], off offset:64
	s_nop 1
	s_nop 0
	v_or_b32_e32 v122, 32, v121
	v_lshlrev_b32_e32 v122, 2, v122
	v_mov_b32_e32 v123, v1
	v_lshl_add_u64 v[124:125], v[128:129], 0, v[122:123]
	v_or_b32_e32 v124, 48, v121
	v_lshlrev_b32_e32 v124, 2, v124
	v_mov_b32_e32 v125, v1
	s_waitcnt vmcnt(12)
	v_pk_fma_f32 v[136:137], v[136:137], v[228:229], v[182:183]
	v_pk_fma_f32 v[134:135], v[134:135], v[226:227], v[180:181]
	global_store_dwordx4 v[126:127], v[134:137], off offset:128
	s_nop 1
	s_nop 0
	v_lshl_add_u64 v[136:137], v[128:129], 0, v[124:125]
	s_waitcnt vmcnt(11)
	v_pk_fma_f32 v[116:117], v[116:117], v[232:233], v[186:187]
	v_pk_fma_f32 v[114:115], v[114:115], v[230:231], v[184:185]
	global_store_dwordx4 v[126:127], v[114:117], off offset:192
	s_nop 1
	s_nop 0
	v_or_b32_e32 v114, 64, v121
	v_lshlrev_b32_e32 v114, 2, v114
	v_mov_b32_e32 v115, v1
	v_lshl_add_u64 v[116:117], v[128:129], 0, v[114:115]
	s_waitcnt vmcnt(10)
	v_pk_fma_f32 v[112:113], v[112:113], v[236:237], v[190:191]
	v_pk_fma_f32 v[110:111], v[110:111], v[234:235], v[188:189]
	global_store_dwordx4 v[126:127], v[110:113], off offset:256
	s_nop 1
	s_nop 0
	v_or_b32_e32 v110, 0x50, v121
	v_lshlrev_b32_e32 v110, 2, v110
	v_mov_b32_e32 v111, v1
	v_lshl_add_u64 v[112:113], v[128:129], 0, v[110:111]
	s_waitcnt vmcnt(9)
	v_pk_fma_f32 v[108:109], v[108:109], v[240:241], v[194:195]
	v_pk_fma_f32 v[106:107], v[106:107], v[238:239], v[192:193]
	global_store_dwordx4 v[126:127], v[106:109], off offset:320
	s_nop 1
	s_nop 0
	v_or_b32_e32 v106, 0x60, v121
	v_lshlrev_b32_e32 v106, 2, v106
	v_mov_b32_e32 v107, v1
	v_lshl_add_u64 v[108:109], v[128:129], 0, v[106:107]
	s_waitcnt vmcnt(8)
	v_pk_fma_f32 v[104:105], v[104:105], v[244:245], v[198:199]
	v_pk_fma_f32 v[102:103], v[102:103], v[242:243], v[196:197]
	global_store_dwordx4 v[126:127], v[102:105], off offset:384
	s_nop 1
	s_nop 0
	v_or_b32_e32 v102, 0x70, v121
	v_lshlrev_b32_e32 v102, 2, v102
	v_mov_b32_e32 v103, v1
	v_lshl_add_u64 v[104:105], v[128:129], 0, v[102:103]
	s_waitcnt vmcnt(7)
	v_pk_fma_f32 v[100:101], v[100:101], v[248:249], v[202:203]
	v_pk_fma_f32 v[98:99], v[98:99], v[246:247], v[200:201]
	global_store_dwordx4 v[126:127], v[98:101], off offset:448
	s_nop 1
	s_nop 1
	v_or_b32_e32 v100, 16, v120
	v_ashrrev_i32_e32 v101, 31, v100
	v_lshlrev_b64 v[104:105], 12, v[100:101]
	v_lshl_add_u64 v[104:105], s[88:89], 0, v[104:105]
	v_cmp_gt_i32_e64 s[42:43], s68, v100
	v_cmp_lt_i32_e64 s[0:1], s11, v100
	v_add_u32_e32 v98, 0xffffe010, v120
	v_mov_b64_e32 v[108:109], v[104:105]
	s_cbranch_vccnz .LBB0_675
	s_and_saveexec_b64 s[8:9], s[0:1]
	s_xor_b64 s[0:1], exec, s[8:9]
	s_cbranch_execz .LBB0_672
	v_mov_b32_e32 v99, v1
	v_readlane_b32 s48, v252, 8
	v_lshlrev_b64 v[100:101], 12, v[98:99]
	v_readlane_b32 s50, v252, 10
	v_readlane_b32 s51, v252, 11
	v_readlane_b32 s49, v252, 9
	v_readlane_b32 s52, v252, 12
	v_lshl_add_u64 v[108:109], s[50:51], 0, v[100:101]
	v_readlane_b32 s53, v252, 13
	v_readlane_b32 s54, v252, 14
	v_readlane_b32 s55, v252, 15
	v_readlane_b32 s56, v252, 16
	v_readlane_b32 s57, v252, 17
	v_readlane_b32 s58, v252, 18
	v_readlane_b32 s59, v252, 19
	v_readlane_b32 s60, v252, 20
	v_readlane_b32 s61, v252, 21
	v_readlane_b32 s62, v252, 22
	v_readlane_b32 s63, v252, 23

.LBB0_675:
	v_lshrrev_b32_e32 v98, 12, v98
	v_add_u32_e32 v98, 1, v98
	v_cndmask_b32_e64 v98, v98, 0, s[42:43]
	v_add_u32_e32 v100, s34, v98
	v_mov_b64_e32 v[98:99], s[20:21]
	v_mad_u64_u32 v[98:99], s[0:1], v100, s29, v[98:99]
	v_lshl_add_u64 v[98:99], v[98:99], 0, s[8:9]
	v_lshl_add_u64 v[100:101], v[108:109], 0, v[0:1]
	v_lshl_add_u64 v[108:109], v[98:99], 0, v[0:1]
	global_load_dwordx4 v[170:173], v[100:101], off
	global_load_dwordx4 v[204:207], v[108:109], off
	global_load_dwordx4 v[174:177], v[100:101], off offset:64
	global_load_dwordx4 v[216:219], v[108:109], off offset:64
	global_load_dwordx4 v[180:183], v[100:101], off offset:128
	global_load_dwordx4 v[226:229], v[108:109], off offset:128
	global_load_dwordx4 v[184:187], v[100:101], off offset:192
	global_load_dwordx4 v[230:233], v[108:109], off offset:192
	global_load_dwordx4 v[188:191], v[100:101], off offset:256
	global_load_dwordx4 v[234:237], v[108:109], off offset:256
	global_load_dwordx4 v[192:195], v[100:101], off offset:320
	global_load_dwordx4 v[238:241], v[108:109], off offset:320
	global_load_dwordx4 v[196:199], v[100:101], off offset:384
	global_load_dwordx4 v[242:245], v[108:109], off offset:384
	global_load_dwordx4 v[200:203], v[100:101], off offset:448
	global_load_dwordx4 v[246:249], v[108:109], off offset:448
	s_and_b64 vcc, exec, s[40:41]
	s_waitcnt vmcnt(14)
	v_pk_fma_f32 v[128:129], v[96:97], v[206:207], v[172:173]
	v_pk_fma_f32 v[126:127], v[94:95], v[204:205], v[170:171]
	v_lshl_add_u64 v[94:95], v[104:105], 0, v[0:1]
	global_store_dwordx4 v[94:95], v[126:129], off
	s_nop 1
	v_lshl_add_u64 v[96:97], v[98:99], 0, v[118:119]
	v_lshl_add_u64 v[96:97], v[98:99], 0, v[122:123]
	s_waitcnt vmcnt(13)
	v_pk_fma_f32 v[92:93], v[92:93], v[218:219], v[176:177]
	v_pk_fma_f32 v[90:91], v[90:91], v[216:217], v[174:175]
	global_store_dwordx4 v[94:95], v[90:93], off offset:64
	s_nop 1
	s_nop 0
	s_waitcnt vmcnt(12)
	v_pk_fma_f32 v[88:89], v[88:89], v[228:229], v[182:183]
	v_pk_fma_f32 v[86:87], v[86:87], v[226:227], v[180:181]
	global_store_dwordx4 v[94:95], v[86:89], off offset:128
	s_nop 1
	v_lshl_add_u64 v[90:91], v[98:99], 0, v[124:125]
	s_nop 0
	s_waitcnt vmcnt(11)
	v_pk_fma_f32 v[84:85], v[84:85], v[232:233], v[186:187]
	v_pk_fma_f32 v[82:83], v[82:83], v[230:231], v[184:185]
	global_store_dwordx4 v[94:95], v[82:85], off offset:192
	s_nop 1
	v_lshl_add_u64 v[86:87], v[98:99], 0, v[114:115]
	s_nop 0
	s_waitcnt vmcnt(10)
	v_pk_fma_f32 v[80:81], v[80:81], v[236:237], v[190:191]
	v_pk_fma_f32 v[78:79], v[78:79], v[234:235], v[188:189]
	global_store_dwordx4 v[94:95], v[78:81], off offset:256
	s_nop 1
	v_lshl_add_u64 v[82:83], v[98:99], 0, v[110:111]
	s_nop 0
	s_waitcnt vmcnt(9)
	v_pk_fma_f32 v[76:77], v[76:77], v[240:241], v[194:195]
	v_pk_fma_f32 v[74:75], v[74:75], v[238:239], v[192:193]
	global_store_dwordx4 v[94:95], v[74:77], off offset:320
	s_nop 1
	v_lshl_add_u64 v[78:79], v[98:99], 0, v[106:107]
	s_nop 0
	s_waitcnt vmcnt(8)
	v_pk_fma_f32 v[72:73], v[72:73], v[244:245], v[198:199]
	v_pk_fma_f32 v[70:71], v[70:71], v[242:243], v[196:197]
	global_store_dwordx4 v[94:95], v[70:73], off offset:384
	s_nop 1
	v_lshl_add_u64 v[74:75], v[98:99], 0, v[102:103]
	s_nop 0
	s_waitcnt vmcnt(7)
	v_pk_fma_f32 v[66:67], v[66:67], v[246:247], v[200:201]
	v_or_b32_e32 v70, 32, v120
	v_pk_fma_f32 v[68:69], v[68:69], v[248:249], v[202:203]
	v_ashrrev_i32_e32 v71, 31, v70
	global_store_dwordx4 v[94:95], v[66:69], off offset:448
	s_nop 1
	v_cmp_gt_i32_e64 s[42:43], s68, v70
	v_cmp_lt_i32_e64 s[0:1], s11, v70
	v_lshlrev_b64 v[66:67], 12, v[70:71]
	v_lshl_add_u64 v[66:67], s[88:89], 0, v[66:67]
	v_add_u32_e32 v68, 0xffffe020, v120
	v_mov_b64_e32 v[72:73], v[66:67]
	s_cbranch_vccnz .LBB0_681
	s_and_saveexec_b64 s[8:9], s[0:1]
	s_xor_b64 s[0:1], exec, s[8:9]
	s_cbranch_execz .LBB0_678
	v_mov_b32_e32 v69, v1
	v_readlane_b32 s48, v252, 8
	v_lshlrev_b64 v[70:71], 12, v[68:69]
	v_readlane_b32 s50, v252, 10
	v_readlane_b32 s51, v252, 11
	v_readlane_b32 s49, v252, 9
	v_readlane_b32 s52, v252, 12
	v_lshl_add_u64 v[72:73], s[50:51], 0, v[70:71]
	v_readlane_b32 s53, v252, 13
	v_readlane_b32 s54, v252, 14
	v_readlane_b32 s55, v252, 15
	v_readlane_b32 s56, v252, 16
	v_readlane_b32 s57, v252, 17
	v_readlane_b32 s58, v252, 18
	v_readlane_b32 s59, v252, 19
	v_readlane_b32 s60, v252, 20
	v_readlane_b32 s61, v252, 21
	v_readlane_b32 s62, v252, 22
	v_readlane_b32 s63, v252, 23

.LBB0_681:
	v_lshrrev_b32_e32 v68, 12, v68
	v_add_u32_e32 v68, 1, v68
	v_cndmask_b32_e64 v68, v68, 0, s[42:43]
	v_add_u32_e32 v70, s34, v68
	v_mov_b64_e32 v[68:69], s[20:21]
	v_mad_u64_u32 v[68:69], s[0:1], v70, s29, v[68:69]
	v_lshl_add_u64 v[76:77], v[68:69], 0, s[8:9]
	v_lshl_add_u64 v[78:79], v[72:73], 0, v[0:1]
	v_lshl_add_u64 v[72:73], v[76:77], 0, v[0:1]
	v_lshl_add_u64 v[80:81], v[66:67], 0, v[0:1]
	global_load_dwordx4 v[170:173], v[78:79], off
	global_load_dwordx4 v[204:207], v[72:73], off
	global_load_dwordx4 v[174:177], v[78:79], off offset:64
	global_load_dwordx4 v[216:219], v[72:73], off offset:64
	global_load_dwordx4 v[180:183], v[78:79], off offset:128
	global_load_dwordx4 v[226:229], v[72:73], off offset:128
	global_load_dwordx4 v[184:187], v[78:79], off offset:192
	global_load_dwordx4 v[230:233], v[72:73], off offset:192
	global_load_dwordx4 v[188:191], v[78:79], off offset:256
	global_load_dwordx4 v[234:237], v[72:73], off offset:256
	global_load_dwordx4 v[192:195], v[78:79], off offset:320
	global_load_dwordx4 v[238:241], v[72:73], off offset:320
	global_load_dwordx4 v[196:199], v[78:79], off offset:384
	global_load_dwordx4 v[242:245], v[72:73], off offset:384
	global_load_dwordx4 v[200:203], v[78:79], off offset:448
	global_load_dwordx4 v[246:249], v[72:73], off offset:448
	v_mov_b32_e32 v119, v1
	v_lshl_add_u64 v[66:67], v[76:77], 0, v[118:119]
	v_mov_b32_e32 v123, v1
	v_mov_b32_e32 v125, v1
	v_mov_b32_e32 v115, v1
	v_mov_b32_e32 v111, v1
	v_mov_b32_e32 v107, v1
	v_mov_b32_e32 v103, v1
	s_and_b64 vcc, exec, s[40:41]
	s_waitcnt vmcnt(14)
	v_pk_fma_f32 v[64:65], v[64:65], v[206:207], v[172:173]
	v_pk_fma_f32 v[62:63], v[62:63], v[204:205], v[170:171]
	global_store_dwordx4 v[80:81], v[62:65], off
	s_nop 1
	s_nop 0
	v_lshl_add_u64 v[70:71], v[76:77], 0, v[122:123]
	s_waitcnt vmcnt(13)
	v_pk_fma_f32 v[60:61], v[60:61], v[218:219], v[176:177]
	v_pk_fma_f32 v[58:59], v[58:59], v[216:217], v[174:175]
	global_store_dwordx4 v[80:81], v[58:61], off offset:64
	s_nop 1
	s_nop 0
	v_lshl_add_u64 v[66:67], v[76:77], 0, v[124:125]
	s_waitcnt vmcnt(12)
	v_pk_fma_f32 v[56:57], v[56:57], v[228:229], v[182:183]
	v_pk_fma_f32 v[54:55], v[54:55], v[226:227], v[180:181]
	global_store_dwordx4 v[80:81], v[54:57], off offset:128
	s_nop 1
	s_nop 0
	v_lshl_add_u64 v[62:63], v[76:77], 0, v[114:115]
	s_waitcnt vmcnt(11)
	v_pk_fma_f32 v[52:53], v[52:53], v[232:233], v[186:187]
	v_pk_fma_f32 v[50:51], v[50:51], v[230:231], v[184:185]
	global_store_dwordx4 v[80:81], v[50:53], off offset:192
	s_nop 1
	s_nop 0
	v_lshl_add_u64 v[58:59], v[76:77], 0, v[110:111]
	s_waitcnt vmcnt(10)
	v_pk_fma_f32 v[48:49], v[48:49], v[236:237], v[190:191]
	v_pk_fma_f32 v[46:47], v[46:47], v[234:235], v[188:189]
	global_store_dwordx4 v[80:81], v[46:49], off offset:256
	s_nop 1
	s_nop 0
	v_lshl_add_u64 v[54:55], v[76:77], 0, v[106:107]
	s_waitcnt vmcnt(9)
	v_pk_fma_f32 v[44:45], v[44:45], v[240:241], v[194:195]
	v_pk_fma_f32 v[42:43], v[42:43], v[238:239], v[192:193]
	global_store_dwordx4 v[80:81], v[42:45], off offset:320
	s_nop 1
	s_nop 0
	v_lshl_add_u64 v[50:51], v[76:77], 0, v[102:103]
	s_waitcnt vmcnt(8)
	v_pk_fma_f32 v[40:41], v[40:41], v[244:245], v[198:199]
	v_pk_fma_f32 v[38:39], v[38:39], v[242:243], v[196:197]
	global_store_dwordx4 v[80:81], v[38:41], off offset:384
	s_nop 1
	s_nop 0
	v_or_b32_e32 v42, 48, v120
	v_ashrrev_i32_e32 v43, 31, v42
	v_lshlrev_b64 v[38:39], 12, v[42:43]
	v_lshl_add_u64 v[38:39], s[88:89], 0, v[38:39]
	v_add_u32_e32 v40, 0xffffe030, v120
	v_cmp_gt_i32_e64 s[0:1], s68, v42
	v_cmp_lt_i32_e64 s[40:41], s11, v42
	s_waitcnt vmcnt(7)
	v_pk_fma_f32 v[36:37], v[36:37], v[248:249], v[202:203]
	v_pk_fma_f32 v[34:35], v[34:35], v[246:247], v[200:201]
	global_store_dwordx4 v[80:81], v[34:37], off offset:448
	s_nop 1
	s_nop 1
	v_mov_b64_e32 v[34:35], v[38:39]
	s_cbranch_vccnz .LBB0_658
	s_and_saveexec_b64 s[8:9], s[40:41]
	s_xor_b64 s[8:9], exec, s[8:9]
	s_cbranch_execz .LBB0_684
	v_mov_b32_e32 v41, v1
	v_readlane_b32 s48, v252, 8
	v_lshlrev_b64 v[34:35], 12, v[40:41]
	v_readlane_b32 s50, v252, 10
	v_readlane_b32 s51, v252, 11
	v_readlane_b32 s49, v252, 9
	v_readlane_b32 s52, v252, 12
	v_lshl_add_u64 v[34:35], s[50:51], 0, v[34:35]
	v_readlane_b32 s53, v252, 13
	v_readlane_b32 s54, v252, 14
	v_readlane_b32 s55, v252, 15
	v_readlane_b32 s56, v252, 16
	v_readlane_b32 s57, v252, 17
	v_readlane_b32 s58, v252, 18
	v_readlane_b32 s59, v252, 19
	v_readlane_b32 s60, v252, 20
	v_readlane_b32 s61, v252, 21
	v_readlane_b32 s62, v252, 22
	v_readlane_b32 s63, v252, 23
